# sample in-proj: per-workgroup rotation of the column-slab order; out-proj K loop started at a per-workgroup K offset (wrap-around) to spread L2 accesses
# speedup vs baseline: 1.0466x; 1.0049x over previous
.LBB0_605:
	s_and_b32 s6, s5, 7
	s_mov_b32 s0, s4
	s_ashr_i32 s1, s5, 8
	s_bfe_u32 s4, s5, 0x50003
	s_mul_i32 s7, s4, 11
	s_lshr_b32 s7, s7, 5
	s_mul_i32 s7, s7, 3
	s_sub_i32 s7, s4, s7
	s_add_i32 s1, s1, s7
	s_cmp_gt_u32 s1, 2
	s_cselect_b32 s7, 3, 0
	s_sub_i32 s1, s1, s7
	s_mul_i32 s6, s6, 3
	s_mul_i32 s7, s4, 24
	s_add_i32 s1, s6, s1
	s_add_i32 s1, s1, s7
	s_mul_hi_i32 s6, s1, 0x2aaaaaab
	s_lshr_b32 s7, s6, 31
	s_ashr_i32 s6, s6, 2
	s_add_i32 s6, s6, s7
	s_mov_b64 s[10:11], s[42:43]
	v_mov_b32_e32 v16, v224
	s_cmp_eq_u32 s4, s0
	s_nop 0
	v_readfirstlane_b32 s0, v16
	s_cbranch_scc1 .LBB0_607
	s_lshl_b32 s8, s6, 1
	s_ashr_i32 s9, s8, 31
	s_lshl_b64 s[8:9], s[8:9], 15
	s_add_u32 s8, s10, s8
	s_addc_u32 s9, s11, s9
	v_ashrrev_i32_e32 v17, 31, v16
	v_lshl_add_u64 v[26:27], v[16:17], 4, s[8:9]
	v_add_co_u32_e32 v0, vcc, 0x14001000, v26
	v_lshl_add_u32 v17, v16, 4, 0
	s_nop 0
	v_addc_co_u32_e32 v1, vcc, 0, v27, vcc
	v_add_co_u32_e32 v4, vcc, 0x14003000, v26
	v_add_u32_e32 v34, 0x8000, v17
	s_nop 0
	v_addc_co_u32_e32 v5, vcc, 0, v27, vcc
	v_add_co_u32_e32 v8, vcc, 0x14005000, v26
	global_load_dwordx4 v[0:3], v[0:1], off
	s_nop 0
	global_load_dwordx4 v[4:7], v[4:5], off
	v_addc_co_u32_e32 v9, vcc, 0, v27, vcc
	v_add_co_u32_e32 v12, vcc, 0x14007000, v26
	s_nop 1
	v_addc_co_u32_e32 v13, vcc, 0, v27, vcc
	v_add_co_u32_e32 v18, vcc, 0x14009000, v26
	global_load_dwordx4 v[8:11], v[8:9], off
	s_nop 0
	global_load_dwordx4 v[12:15], v[12:13], off
	v_addc_co_u32_e32 v19, vcc, 0, v27, vcc
	v_add_co_u32_e32 v22, vcc, 0x1400b000, v26
	s_nop 1
	v_addc_co_u32_e32 v23, vcc, 0, v27, vcc
	v_add_co_u32_e32 v28, vcc, 0x1400d000, v26
	global_load_dwordx4 v[18:21], v[18:19], off
	s_nop 0
	global_load_dwordx4 v[22:25], v[22:23], off
	v_addc_co_u32_e32 v29, vcc, 0, v27, vcc
	v_add_co_u32_e32 v30, vcc, 0x1400f000, v26
	s_nop 1
	v_addc_co_u32_e32 v31, vcc, 0, v27, vcc
	global_load_dwordx4 v[26:29], v[28:29], off
	s_nop 0
	global_load_dwordx4 v[30:33], v[30:31], off
	s_waitcnt vmcnt(0)
	ds_write_b128 v17, v[0:3] offset:32768
	ds_write_b128 v17, v[4:7] offset:40960
	ds_write_b128 v17, v[8:11] offset:49152
	ds_write_b128 v17, v[12:15] offset:57344
	ds_write_b128 v34, v[18:21] offset:32768
	ds_write_b128 v34, v[22:25] offset:40960
	ds_write_b128 v34, v[26:29] offset:49152
	ds_write_b128 v34, v[30:33] offset:57344
	s_waitcnt lgkmcnt(0)
	s_barrier

.LBB0_861:
	s_mov_b64 s[20:21], s[42:43]
	v_readlane_b32 s92, v254, 0
	s_bfe_u32 s92, s92, 0x40003
	s_lshl_b32 s94, s92, 11
	s_mov_b32 s95, 0
	s_sub_i32 s93, 15, s92
	s_lshl_b32 s93, s93, 1
	s_mov_b32 s96, 0xffff8000
	s_mov_b32 s97, -1
	s_add_u32 s5, s20, s2
	s_addc_u32 s9, s21, 0
	s_lshl_b32 s0, s3, 2
	s_ashr_i32 s1, s0, 31
	s_lshl_b64 s[0:1], s[0:1], 15
	v_mov_b32_e32 v214, v224
	s_add_u32 s0, s20, s0
	s_addc_u32 s1, s21, s1
	v_ashrrev_i32_e32 v215, 31, v214
	v_lshl_add_u64 v[60:61], v[214:215], 4, s[0:1]
	s_mov_b32 s0, 0xfe01000
	s_waitcnt vmcnt(10)
	v_add_co_u32_e32 v0, vcc, s0, v60
	s_mov_b32 s0, 0xfe03000
	s_nop 0
	v_addc_co_u32_e32 v1, vcc, 0, v61, vcc
	v_add_co_u32_e32 v4, vcc, s0, v60
	s_mov_b32 s0, 0xfe05000
	s_nop 0
	v_addc_co_u32_e32 v5, vcc, 0, v61, vcc
	v_add_co_u32_e32 v8, vcc, s0, v60
	s_mov_b32 s0, 0xfe07000
	s_nop 0
	v_addc_co_u32_e32 v9, vcc, 0, v61, vcc
	v_add_co_u32_e32 v12, vcc, s0, v60
	s_mov_b32 s0, 0xfe09000
	s_nop 0
	v_addc_co_u32_e32 v13, vcc, 0, v61, vcc
	v_add_co_u32_e32 v16, vcc, s0, v60
	s_mov_b32 s0, 0xfe0b000
	s_nop 0
	v_addc_co_u32_e32 v17, vcc, 0, v61, vcc
	v_add_co_u32_e32 v20, vcc, s0, v60
	s_mov_b32 s0, 0xfe0d000
	s_nop 0
	v_addc_co_u32_e32 v21, vcc, 0, v61, vcc
	v_add_co_u32_e32 v24, vcc, s0, v60
	s_mov_b32 s0, 0xfe0f000
	s_nop 0
	v_addc_co_u32_e32 v25, vcc, 0, v61, vcc
	v_add_co_u32_e32 v28, vcc, s0, v60
	s_mov_b32 s0, 0xfe11000
	s_nop 0
	v_addc_co_u32_e32 v29, vcc, 0, v61, vcc
	v_add_co_u32_e32 v32, vcc, s0, v60
	s_mov_b32 s0, 0xfe13000
	s_nop 0
	v_addc_co_u32_e32 v33, vcc, 0, v61, vcc
	v_add_co_u32_e32 v36, vcc, s0, v60
	s_mov_b32 s0, 0xfe15000
	s_nop 0
	v_addc_co_u32_e32 v37, vcc, 0, v61, vcc
	v_add_co_u32_e32 v40, vcc, s0, v60
	s_mov_b32 s0, 0xfe17000
	s_nop 0
	v_addc_co_u32_e32 v41, vcc, 0, v61, vcc
	v_add_co_u32_e32 v44, vcc, s0, v60
	s_mov_b32 s0, 0xfe19000
	s_nop 0
	v_addc_co_u32_e32 v45, vcc, 0, v61, vcc
	global_load_dwordx4 v[0:3], v[0:1], off nt
	s_nop 0
	global_load_dwordx4 v[4:7], v[4:5], off nt
	s_nop 0
	global_load_dwordx4 v[8:11], v[8:9], off nt
	s_nop 0
	global_load_dwordx4 v[12:15], v[12:13], off nt
	s_nop 0
	global_load_dwordx4 v[16:19], v[16:17], off nt
	s_nop 0
	global_load_dwordx4 v[20:23], v[20:21], off nt
	s_nop 0
	global_load_dwordx4 v[24:27], v[24:25], off nt
	s_nop 0
	global_load_dwordx4 v[28:31], v[28:29], off nt
	v_add_co_u32_e32 v48, vcc, s0, v60
	s_mov_b32 s0, 0xfe1b000
	s_nop 0
	v_addc_co_u32_e32 v49, vcc, 0, v61, vcc
	global_load_dwordx4 v[32:35], v[32:33], off nt
	s_nop 0
	global_load_dwordx4 v[36:39], v[36:37], off nt
	v_add_co_u32_e32 v52, vcc, s0, v60
	s_mov_b32 s0, 0xfe1d000
	s_nop 0
	v_addc_co_u32_e32 v53, vcc, 0, v61, vcc
	global_load_dwordx4 v[40:43], v[40:41], off nt
	s_nop 0
	global_load_dwordx4 v[44:47], v[44:45], off nt
	v_add_co_u32_e32 v56, vcc, s0, v60
	s_mov_b32 s0, 0xfe1f000
	s_nop 0
	v_addc_co_u32_e32 v57, vcc, 0, v61, vcc
	global_load_dwordx4 v[48:51], v[48:49], off nt
	s_nop 0
	global_load_dwordx4 v[52:55], v[52:53], off nt
	v_add_co_u32_e32 v60, vcc, s0, v60
	global_load_dwordx4 v[56:59], v[56:57], off nt
	s_nop 0
	v_addc_co_u32_e32 v61, vcc, 0, v61, vcc
	global_load_dwordx4 v[60:63], v[60:61], off nt
	v_lshl_add_u32 v64, v214, 4, 0
	v_readfirstlane_b32 s0, v214
	s_waitcnt vmcnt(15)
	ds_write_b128 v64, v[0:3]
	s_waitcnt vmcnt(14)
	ds_write_b128 v64, v[4:7] offset:8192
	s_waitcnt vmcnt(13)
	ds_write_b128 v64, v[8:11] offset:16384
	s_waitcnt vmcnt(12)
	ds_write_b128 v64, v[12:15] offset:24576
	s_waitcnt vmcnt(11)
	ds_write_b128 v64, v[16:19] offset:32768
	s_waitcnt vmcnt(10)
	ds_write_b128 v64, v[20:23] offset:40960
	s_waitcnt vmcnt(9)
	ds_write_b128 v64, v[24:27] offset:49152
	s_waitcnt vmcnt(8)
	ds_write_b128 v64, v[28:31] offset:57344
	v_add_u32_e32 v0, 0x10000, v64
	s_ashr_i32 s4, s0, 6
	s_lshl_b32 s6, s4, 3
	s_ashr_i32 s7, s6, 31
	s_waitcnt vmcnt(7)
	ds_write_b128 v0, v[32:35]
	v_add_u32_e32 v0, 0x12000, v64
	s_waitcnt vmcnt(6)
	ds_write_b128 v0, v[36:39]
	v_add_u32_e32 v0, 0x14000, v64
	s_lshl_b64 s[6:7], s[6:7], 15
	v_and_b32_e32 v204, 63, v214
	s_waitcnt vmcnt(5)
	ds_write_b128 v0, v[40:43]
	v_add_u32_e32 v0, 0x16000, v64
	s_waitcnt vmcnt(4)
	ds_write_b128 v0, v[44:47]
	v_add_u32_e32 v0, 0x18000, v64
	s_add_u32 s8, s5, s6
	s_addc_u32 s9, s9, s7
	s_waitcnt vmcnt(3)
	ds_write_b128 v0, v[48:51]
	v_add_u32_e32 v0, 0x1a000, v64
	s_waitcnt vmcnt(2)
	ds_write_b128 v0, v[52:55]
	v_add_u32_e32 v0, 0x1c000, v64
	v_lshlrev_b32_e32 v196, 4, v204
	s_waitcnt vmcnt(1)
	ds_write_b128 v0, v[56:59]
	v_add_u32_e32 v0, 0x1e000, v64
	v_lshl_add_u64 v[16:17], s[8:9], 0, v[196:197]
	v_lshl_add_u64 v[16:17], v[16:17], 0, s[94:95]
	s_waitcnt vmcnt(0)
	ds_write_b128 v0, v[60:63]
	v_add_co_u32_e32 v0, vcc, s82, v16
	s_waitcnt lgkmcnt(0)
	s_nop 0
	v_addc_co_u32_e32 v1, vcc, 0, v17, vcc
	v_add_co_u32_e32 v4, vcc, s83, v16
	s_barrier
	s_nop 0
	v_addc_co_u32_e32 v5, vcc, 0, v17, vcc
	v_add_co_u32_e32 v8, vcc, s84, v16
	s_nop 1
	v_addc_co_u32_e32 v9, vcc, 0, v17, vcc
	v_add_co_u32_e32 v12, vcc, s85, v16
	global_load_dwordx4 v[0:3], v[0:1], off
	s_nop 0
	global_load_dwordx4 v[4:7], v[4:5], off
	v_addc_co_u32_e32 v13, vcc, 0, v17, vcc
	v_add_co_u32_e32 v18, vcc, s86, v16
	global_load_dwordx4 v[8:11], v[8:9], off
	s_nop 0
	global_load_dwordx4 v[12:15], v[12:13], off
	v_addc_co_u32_e32 v19, vcc, 0, v17, vcc
	v_add_co_u32_e32 v20, vcc, s87, v16
	s_mov_b64 s[8:9], 0x1800000
	s_nop 0
	v_addc_co_u32_e32 v21, vcc, 0, v17, vcc
	global_load_dwordx4 v[144:147], v[18:19], off
	global_load_dwordx4 v[148:151], v[20:21], off
	v_add_co_u32_e32 v18, vcc, s88, v16
	s_mov_b32 s0, 0x1838000
	s_nop 0
	v_addc_co_u32_e32 v19, vcc, 0, v17, vcc
	v_lshl_add_u64 v[202:203], v[16:17], 0, s[8:9]
	v_add_co_u32_e32 v16, vcc, s0, v16
	v_readlane_b32 s8, v255, 40
	s_nop 0
	v_addc_co_u32_e32 v17, vcc, 0, v17, vcc
	global_load_dwordx4 v[152:155], v[18:19], off
	global_load_dwordx4 v[156:159], v[16:17], off
	v_readlane_b32 s9, v255, 41
	s_add_u32 s0, s20, s8
	s_addc_u32 s5, s21, s9
	s_add_u32 s10, s0, s6
	s_addc_u32 s11, s5, s7
	v_readlane_b32 s8, v255, 42
	v_readlane_b32 s9, v255, 43
	s_add_u32 s0, s20, s8
	s_addc_u32 s5, s21, s9
	v_add_u32_e32 v244, 0, v196
	s_add_u32 s24, s0, s6
	v_mov_b32_e32 v80, 0
	s_mov_b32 s1, 0
	s_addc_u32 s25, s5, s7
	s_movk_i32 s0, 0x400
	v_mov_b32_e32 v205, v244
	s_add_u32 s10, s10, s94
	s_addc_u32 s11, s11, 0
	s_add_u32 s24, s24, s94
	s_addc_u32 s25, s25, 0
	v_add_u32_e32 v205, s94, v205
	v_mov_b32_e32 v81, v80
	v_mov_b32_e32 v82, v80
	v_mov_b32_e32 v83, v80
	v_mov_b32_e32 v84, v80
	v_mov_b32_e32 v85, v80
	v_mov_b32_e32 v86, v80
	v_mov_b32_e32 v87, v80
	v_mov_b32_e32 v88, v80
	v_mov_b32_e32 v89, v80
	v_mov_b32_e32 v90, v80
	v_mov_b32_e32 v91, v80
	v_mov_b32_e32 v92, v80
	v_mov_b32_e32 v93, v80
	v_mov_b32_e32 v94, v80
	v_mov_b32_e32 v95, v80
	v_mov_b32_e32 v96, v80
	v_mov_b32_e32 v97, v80
	v_mov_b32_e32 v98, v80
	v_mov_b32_e32 v99, v80
	v_mov_b32_e32 v100, v80
	v_mov_b32_e32 v101, v80
	v_mov_b32_e32 v102, v80
	v_mov_b32_e32 v103, v80
	v_mov_b32_e32 v104, v80
	v_mov_b32_e32 v105, v80
	v_mov_b32_e32 v106, v80
	v_mov_b32_e32 v107, v80
	v_mov_b32_e32 v108, v80
	v_mov_b32_e32 v109, v80
	v_mov_b32_e32 v110, v80
	v_mov_b32_e32 v111, v80
	v_mov_b32_e32 v112, v80
	v_mov_b32_e32 v113, v80
	v_mov_b32_e32 v114, v80
	v_mov_b32_e32 v115, v80
	v_mov_b32_e32 v124, v80
	v_mov_b32_e32 v125, v80
	v_mov_b32_e32 v126, v80
	v_mov_b32_e32 v127, v80
	v_mov_b32_e32 v136, v80
	v_mov_b32_e32 v137, v80
	v_mov_b32_e32 v138, v80
	v_mov_b32_e32 v139, v80
	v_mov_b32_e32 v140, v80
	v_mov_b32_e32 v141, v80
	v_mov_b32_e32 v142, v80
	v_mov_b32_e32 v143, v80
	v_mov_b32_e32 v116, v80
	v_mov_b32_e32 v117, v80
	v_mov_b32_e32 v118, v80
	v_mov_b32_e32 v119, v80
	v_mov_b32_e32 v120, v80
	v_mov_b32_e32 v121, v80
	v_mov_b32_e32 v122, v80
	v_mov_b32_e32 v123, v80
	v_mov_b32_e32 v128, v80
	v_mov_b32_e32 v129, v80
	v_mov_b32_e32 v130, v80
	v_mov_b32_e32 v131, v80
	v_mov_b32_e32 v132, v80
	v_mov_b32_e32 v133, v80
	v_mov_b32_e32 v134, v80
	v_mov_b32_e32 v135, v80
	v_mov_b32_e32 v16, v80
	v_mov_b32_e32 v17, v80
	v_mov_b32_e32 v18, v80
	v_mov_b32_e32 v19, v80
	v_mov_b32_e32 v20, v80
	v_mov_b32_e32 v21, v80
	v_mov_b32_e32 v22, v80
	v_mov_b32_e32 v23, v80
	v_mov_b32_e32 v24, v80
	v_mov_b32_e32 v25, v80
	v_mov_b32_e32 v26, v80
	v_mov_b32_e32 v27, v80
	v_mov_b32_e32 v28, v80
	v_mov_b32_e32 v29, v80
	v_mov_b32_e32 v30, v80
	v_mov_b32_e32 v31, v80
	v_mov_b32_e32 v32, v80
	v_mov_b32_e32 v33, v80
	v_mov_b32_e32 v34, v80
	v_mov_b32_e32 v35, v80
	v_mov_b32_e32 v36, v80
	v_mov_b32_e32 v37, v80
	v_mov_b32_e32 v38, v80
	v_mov_b32_e32 v39, v80
	v_mov_b32_e32 v40, v80
	v_mov_b32_e32 v41, v80
	v_mov_b32_e32 v42, v80
	v_mov_b32_e32 v43, v80
	v_mov_b32_e32 v44, v80
	v_mov_b32_e32 v45, v80
	v_mov_b32_e32 v46, v80
	v_mov_b32_e32 v47, v80
	v_mov_b32_e32 v48, v80
	v_mov_b32_e32 v49, v80
	v_mov_b32_e32 v50, v80
	v_mov_b32_e32 v51, v80
	v_mov_b32_e32 v52, v80
	v_mov_b32_e32 v53, v80
	v_mov_b32_e32 v54, v80
	v_mov_b32_e32 v55, v80
	v_mov_b32_e32 v56, v80
	v_mov_b32_e32 v57, v80
	v_mov_b32_e32 v58, v80
	v_mov_b32_e32 v59, v80
	v_mov_b32_e32 v60, v80
	v_mov_b32_e32 v61, v80
	v_mov_b32_e32 v62, v80
	v_mov_b32_e32 v63, v80
	v_mov_b32_e32 v64, v80
	v_mov_b32_e32 v65, v80
	v_mov_b32_e32 v66, v80
	v_mov_b32_e32 v67, v80
	v_mov_b32_e32 v68, v80
	v_mov_b32_e32 v69, v80
	v_mov_b32_e32 v70, v80
	v_mov_b32_e32 v71, v80
	v_mov_b32_e32 v72, v80
	v_mov_b32_e32 v73, v80
	v_mov_b32_e32 v74, v80
	v_mov_b32_e32 v75, v80
	v_mov_b32_e32 v76, v80
	v_mov_b32_e32 v77, v80
	v_mov_b32_e32 v78, v80
	v_mov_b32_e32 v79, v80
.LBB0_862:
	v_lshl_add_u64 v[184:185], s[24:25], 0, v[196:197]
	v_add_co_u32_e32 v160, vcc, s82, v184
	v_lshl_add_u64 v[188:189], s[10:11], 0, v[196:197]
	s_nop 0
	v_addc_co_u32_e32 v161, vcc, 0, v185, vcc
	v_add_co_u32_e32 v164, vcc, s83, v184
	s_nop 1
	v_addc_co_u32_e32 v165, vcc, 0, v185, vcc
	v_add_co_u32_e32 v168, vcc, s84, v184
	global_load_dwordx4 v[160:163], v[160:161], off offset:1024
	s_nop 0
	global_load_dwordx4 v[164:167], v[164:165], off offset:1024
	v_addc_co_u32_e32 v169, vcc, 0, v185, vcc
	v_add_co_u32_e32 v172, vcc, s85, v184
	s_nop 1
	v_addc_co_u32_e32 v173, vcc, 0, v185, vcc
	v_add_co_u32_e32 v176, vcc, s86, v184
	global_load_dwordx4 v[168:171], v[168:169], off offset:1024
	s_nop 0
	global_load_dwordx4 v[172:175], v[172:173], off offset:1024
	v_addc_co_u32_e32 v177, vcc, 0, v185, vcc
	v_add_co_u32_e32 v180, vcc, s87, v184
	s_nop 1
	v_addc_co_u32_e32 v181, vcc, 0, v185, vcc
	v_add_co_u32_e32 v184, vcc, s88, v184
	global_load_dwordx4 v[176:179], v[176:177], off offset:1024
	s_nop 0
	global_load_dwordx4 v[180:183], v[180:181], off offset:1024
	v_addc_co_u32_e32 v185, vcc, 0, v185, vcc
	global_load_dwordx4 v[184:187], v[184:185], off offset:1024
	s_nop 0
	global_load_dwordx4 v[188:191], v[188:189], off
	ds_read_b128 v[206:209], v205
	v_add_u32_e32 v210, 0x10000, v205
	s_waitcnt vmcnt(15) lgkmcnt(0)
	v_mfma_f32_16x16x32_bf16 v[140:143], v[0:3], v[206:209], v[140:143]
	s_waitcnt vmcnt(14)
	v_mfma_f32_16x16x32_bf16 v[136:139], v[4:7], v[206:209], v[136:139]
	s_waitcnt vmcnt(13)
	v_mfma_f32_16x16x32_bf16 v[124:127], v[8:11], v[206:209], v[124:127]
	s_waitcnt vmcnt(12)
	v_mfma_f32_16x16x32_bf16 v[112:115], v[12:15], v[206:209], v[112:115]
	s_waitcnt vmcnt(11)
	v_mfma_f32_16x16x32_bf16 v[108:111], v[144:147], v[206:209], v[108:111]
	s_waitcnt vmcnt(10)
	v_mfma_f32_16x16x32_bf16 v[104:107], v[148:151], v[206:209], v[104:107]
	s_waitcnt vmcnt(9)
	v_mfma_f32_16x16x32_bf16 v[100:103], v[152:155], v[206:209], v[100:103]
	s_waitcnt vmcnt(8)
	v_mfma_f32_16x16x32_bf16 v[96:99], v[156:159], v[206:209], v[96:99]
	ds_read_b128 v[206:209], v205 offset:32768
	s_waitcnt lgkmcnt(0)
	v_mfma_f32_16x16x32_bf16 v[92:95], v[0:3], v[206:209], v[92:95]
	v_mfma_f32_16x16x32_bf16 v[88:91], v[4:7], v[206:209], v[88:91]
	v_mfma_f32_16x16x32_bf16 v[84:87], v[8:11], v[206:209], v[84:87]
	v_mfma_f32_16x16x32_bf16 v[80:83], v[12:15], v[206:209], v[80:83]
	v_mfma_f32_16x16x32_bf16 v[116:119], v[144:147], v[206:209], v[116:119]
	v_mfma_f32_16x16x32_bf16 v[120:123], v[148:151], v[206:209], v[120:123]
	v_mfma_f32_16x16x32_bf16 v[128:131], v[152:155], v[206:209], v[128:131]
	v_mfma_f32_16x16x32_bf16 v[132:135], v[156:159], v[206:209], v[132:135]
	ds_read_b128 v[206:209], v210
	v_add_u32_e32 v210, 0x18000, v205
	s_waitcnt lgkmcnt(0)
	v_mfma_f32_16x16x32_bf16 v[16:19], v[0:3], v[206:209], v[16:19]
	v_mfma_f32_16x16x32_bf16 v[20:23], v[4:7], v[206:209], v[20:23]
	v_mfma_f32_16x16x32_bf16 v[24:27], v[8:11], v[206:209], v[24:27]
	v_mfma_f32_16x16x32_bf16 v[28:31], v[12:15], v[206:209], v[28:31]
	v_mfma_f32_16x16x32_bf16 v[32:35], v[144:147], v[206:209], v[32:35]
	v_mfma_f32_16x16x32_bf16 v[36:39], v[148:151], v[206:209], v[36:39]
	v_mfma_f32_16x16x32_bf16 v[40:43], v[152:155], v[206:209], v[40:43]
	v_mfma_f32_16x16x32_bf16 v[44:47], v[156:159], v[206:209], v[44:47]
	ds_read_b128 v[206:209], v210
	s_waitcnt lgkmcnt(0)
	v_mfma_f32_16x16x32_bf16 v[48:51], v[0:3], v[206:209], v[48:51]
	v_mfma_f32_16x16x32_bf16 v[52:55], v[4:7], v[206:209], v[52:55]
	v_mfma_f32_16x16x32_bf16 v[56:59], v[8:11], v[206:209], v[56:59]
	v_mfma_f32_16x16x32_bf16 v[60:63], v[12:15], v[206:209], v[60:63]
	v_mfma_f32_16x16x32_bf16 v[64:67], v[144:147], v[206:209], v[64:67]
	v_mfma_f32_16x16x32_bf16 v[68:71], v[148:151], v[206:209], v[68:71]
	v_mfma_f32_16x16x32_bf16 v[72:75], v[152:155], v[206:209], v[72:75]
	v_mfma_f32_16x16x32_bf16 v[76:79], v[156:159], v[206:209], v[76:79]
	s_cmp_lg_u32 s1, s93
	s_cbranch_scc1 .Lfk_nowrap2
	v_lshl_add_u64 v[202:203], v[202:203], 0, s[96:97]
.Lfk_nowrap2:
	s_add_i32 s5, s1, 2
	s_cmp_lt_u32 s1, 30
	s_cselect_b64 s[6:7], -1, 0
	s_and_b64 vcc, s[6:7], exec
	s_cselect_b32 s22, s0, 0x3e00
	v_lshl_add_u64 v[152:153], s[22:23], 1, v[202:203]
	v_add_co_u32_e64 v4, s[38:39], s73, v152
	s_mov_b32 s1, 0x18000
	s_nop 0
	v_addc_co_u32_e64 v5, s[38:39], 0, v153, s[38:39]
	v_add_co_u32_e64 v8, s[38:39], s72, v152
	global_load_dwordx4 v[0:3], v[152:153], off
	s_nop 0
	global_load_dwordx4 v[4:7], v[4:5], off
	v_addc_co_u32_e64 v9, s[38:39], 0, v153, s[38:39]
	v_add_co_u32_e64 v12, s[38:39], s1, v152
	s_mov_b32 s1, 0x20000
	s_nop 0
	v_addc_co_u32_e64 v13, s[38:39], 0, v153, s[38:39]
	v_add_co_u32_e64 v144, s[38:39], s1, v152
	s_mov_b32 s1, 0x28000
	s_nop 0
	v_addc_co_u32_e64 v145, s[38:39], 0, v153, s[38:39]
	v_add_co_u32_e64 v148, s[38:39], s1, v152
	s_mov_b32 s1, 0x30000
	s_nop 0
	v_addc_co_u32_e64 v149, s[38:39], 0, v153, s[38:39]
	v_add_co_u32_e64 v154, s[38:39], s1, v152
	s_mov_b32 s1, 0x38000
	s_nop 0
	v_addc_co_u32_e64 v155, s[38:39], 0, v153, s[38:39]
	v_add_co_u32_e64 v156, s[38:39], s1, v152
	global_load_dwordx4 v[8:11], v[8:9], off
	s_nop 0
	global_load_dwordx4 v[12:15], v[12:13], off
	v_addc_co_u32_e64 v157, s[38:39], 0, v153, s[38:39]
	global_load_dwordx4 v[144:147], v[144:145], off
	s_nop 0
	global_load_dwordx4 v[148:151], v[148:149], off
	s_nop 0
	global_load_dwordx4 v[152:155], v[154:155], off
	s_nop 0
	global_load_dwordx4 v[156:159], v[156:157], off
	ds_read_b128 v[206:209], v205 offset:1024
	v_add_u32_e32 v210, 0x10400, v205
	s_waitcnt vmcnt(15) lgkmcnt(0)
	v_mfma_f32_16x16x32_bf16 v[140:143], v[160:163], v[206:209], v[140:143]
	s_waitcnt vmcnt(14)
	v_mfma_f32_16x16x32_bf16 v[136:139], v[164:167], v[206:209], v[136:139]
	s_waitcnt vmcnt(13)
	v_mfma_f32_16x16x32_bf16 v[124:127], v[168:171], v[206:209], v[124:127]
	s_waitcnt vmcnt(12)
	v_mfma_f32_16x16x32_bf16 v[112:115], v[172:175], v[206:209], v[112:115]
	s_waitcnt vmcnt(11)
	v_mfma_f32_16x16x32_bf16 v[108:111], v[176:179], v[206:209], v[108:111]
	s_waitcnt vmcnt(10)
	v_mfma_f32_16x16x32_bf16 v[104:107], v[180:183], v[206:209], v[104:107]
	s_waitcnt vmcnt(9)
	v_mfma_f32_16x16x32_bf16 v[100:103], v[184:187], v[206:209], v[100:103]
	s_waitcnt vmcnt(8)
	v_mfma_f32_16x16x32_bf16 v[96:99], v[188:191], v[206:209], v[96:99]
	ds_read_b128 v[206:209], v205 offset:33792
	s_waitcnt lgkmcnt(0)
	v_mfma_f32_16x16x32_bf16 v[92:95], v[160:163], v[206:209], v[92:95]
	v_mfma_f32_16x16x32_bf16 v[88:91], v[164:167], v[206:209], v[88:91]
	v_mfma_f32_16x16x32_bf16 v[84:87], v[168:171], v[206:209], v[84:87]
	v_mfma_f32_16x16x32_bf16 v[80:83], v[172:175], v[206:209], v[80:83]
	v_mfma_f32_16x16x32_bf16 v[116:119], v[176:179], v[206:209], v[116:119]
	v_mfma_f32_16x16x32_bf16 v[120:123], v[180:183], v[206:209], v[120:123]
	v_mfma_f32_16x16x32_bf16 v[128:131], v[184:187], v[206:209], v[128:131]
	v_mfma_f32_16x16x32_bf16 v[132:135], v[188:191], v[206:209], v[132:135]
	ds_read_b128 v[206:209], v210
	v_add_u32_e32 v210, 0x18400, v205
	s_waitcnt lgkmcnt(0)
	v_mfma_f32_16x16x32_bf16 v[16:19], v[160:163], v[206:209], v[16:19]
	v_mfma_f32_16x16x32_bf16 v[20:23], v[164:167], v[206:209], v[20:23]
	v_mfma_f32_16x16x32_bf16 v[24:27], v[168:171], v[206:209], v[24:27]
	v_mfma_f32_16x16x32_bf16 v[28:31], v[172:175], v[206:209], v[28:31]
	v_mfma_f32_16x16x32_bf16 v[32:35], v[176:179], v[206:209], v[32:35]
	v_mfma_f32_16x16x32_bf16 v[36:39], v[180:183], v[206:209], v[36:39]
	v_mfma_f32_16x16x32_bf16 v[40:43], v[184:187], v[206:209], v[40:43]
	v_mfma_f32_16x16x32_bf16 v[44:47], v[188:191], v[206:209], v[44:47]
	ds_read_b128 v[206:209], v210
	s_waitcnt lgkmcnt(0)
	v_mfma_f32_16x16x32_bf16 v[48:51], v[160:163], v[206:209], v[48:51]
	v_mfma_f32_16x16x32_bf16 v[52:55], v[164:167], v[206:209], v[52:55]
	v_mfma_f32_16x16x32_bf16 v[56:59], v[168:171], v[206:209], v[56:59]
	v_mfma_f32_16x16x32_bf16 v[60:63], v[172:175], v[206:209], v[60:63]
	v_mfma_f32_16x16x32_bf16 v[64:67], v[176:179], v[206:209], v[64:67]
	v_mfma_f32_16x16x32_bf16 v[68:71], v[180:183], v[206:209], v[68:71]
	v_mfma_f32_16x16x32_bf16 v[72:75], v[184:187], v[206:209], v[72:75]
	v_mfma_f32_16x16x32_bf16 v[76:79], v[188:191], v[206:209], v[76:79]
	s_addk_i32 s0, 0x400
	s_add_u32 s10, s10, 0x800
	s_addc_u32 s11, s11, 0
	s_add_u32 s24, s24, 0x800
	v_add_u32_e32 v205, 0x800, v205
	s_addc_u32 s25, s25, 0
	s_mov_b32 s1, s5
	s_sub_i32 s99, s5, 2
	s_cmp_lg_u32 s99, s93
	s_cbranch_scc1 .Lfk_nowrap1
	s_add_u32 s10, s10, s96
	s_addc_u32 s11, s11, s97
	s_add_u32 s24, s24, s96
	s_addc_u32 s25, s25, s97
	v_add_u32_e32 v205, s96, v205
.Lfk_nowrap1:
	s_cbranch_vccnz .LBB0_862
	s_ashr_i32 s0, s3, 5
	s_mul_hi_i32 s1, s0, 0xc000
	s_mul_i32 s0, s0, 0xc000
	s_add_u32 s0, s20, s0
	s_addc_u32 s1, s21, s1
	s_add_u32 s0, s0, 0x3900000
	s_addc_u32 s1, s1, 0
	s_add_u32 s5, s0, s50
	s_addc_u32 s6, s1, s51
	s_add_u32 s16, s5, 0x2000
	s_addc_u32 s17, s6, 0
	global_load_dwordx4 v[144:147], v196, s[16:17]
	global_load_dwordx4 v[148:151], v196, s[46:47]
	s_add_u32 s0, s0, s52
	s_addc_u32 s1, s1, s53
	v_lshlrev_b32_e32 v215, 2, v204
	s_add_u32 s10, s0, 0x1000
	v_mov_b32_e32 v176, 0
	s_waitcnt vmcnt(9)
	v_cndmask_b32_e64 v0, 0, 1, s[44:45]
	s_addc_u32 s11, s1, 0
	v_cmp_ne_u32_e64 s[38:39], 1, v0
	s_andn2_b64 vcc, exec, s[44:45]
	v_lshlrev_b32_e32 v220, 2, v215
	v_mov_b32_e32 v178, 0
	v_mov_b32_e32 v179, v176
	v_mov_b32_e32 v180, 0
	v_mov_b32_e32 v181, 0
	v_mov_b32_e32 v0, 0
	v_mov_b32_e32 v1, v176
	v_mov_b32_e32 v2, 0
	v_mov_b32_e32 v3, 0
	s_cbranch_vccnz .LBB0_865
	global_load_dwordx4 v[0:3], v220, s[48:49]
	global_load_dwordx4 v[4:7], v220, s[10:11]
	s_waitcnt vmcnt(0)
	v_pk_add_f32 v[6:7], v[6:7], 1.0 op_sel_hi:[1,0]
	v_pk_add_f32 v[4:5], v[4:5], 1.0 op_sel_hi:[1,0]
	v_pk_mul_f32 v[180:181], v[2:3], v[6:7]
	v_pk_mul_f32 v[178:179], v[0:1], v[4:5]
	global_load_dwordx4 v[0:3], v220, s[0:1]
